# POLL-NOSLEEP: s_sleep 1 removed from the 35 barrier / exchange poll loops (on REL-FIRST)
# speedup vs baseline: 1.0012x; 1.0012x over previous
.LBB0_46:
	global_load_dword v16, v17, s[10:11] sc1
	global_load_dword v1, v17, s[12:13] sc1
	global_load_dword v2, v17, s[14:15] sc1
	global_load_dword v3, v17, s[16:17] sc1
	global_load_dword v4, v17, s[18:19] sc1
	global_load_dword v5, v17, s[20:21] sc1
	global_load_dword v6, v17, s[22:23] sc1
	global_load_dword v7, v17, s[24:25] sc1
	global_load_dword v8, v17, s[26:27] sc1
	global_load_dword v9, v17, s[28:29] sc1
	global_load_dword v10, v17, s[30:31] sc1
	global_load_dword v11, v17, s[36:37] sc1
	global_load_dword v12, v17, s[38:39] sc1
	global_load_dword v13, v17, s[40:41] sc1
	global_load_dword v14, v17, s[42:43] sc1
	global_load_dword v15, v17, s[44:45] sc1
	s_mov_b64 s[46:47], -1
	s_mov_b64 s[48:49], -1
	s_waitcnt vmcnt(14)
	v_add_u32_e32 v18, v1, v16
	s_waitcnt vmcnt(13)
	v_add_u32_e32 v18, v18, v2
	s_waitcnt vmcnt(12)
	v_add_u32_e32 v18, v18, v3
	s_waitcnt vmcnt(11)
	v_add_u32_e32 v18, v18, v4
	s_waitcnt vmcnt(10)
	v_add_u32_e32 v18, v18, v5
	s_waitcnt vmcnt(9)
	v_add_u32_e32 v18, v18, v6
	s_waitcnt vmcnt(8)
	v_add_u32_e32 v18, v18, v7
	s_waitcnt vmcnt(7)
	v_add_u32_e32 v18, v18, v8
	s_waitcnt vmcnt(6)
	v_add_u32_e32 v18, v18, v9
	s_waitcnt vmcnt(5)
	v_add_u32_e32 v18, v18, v10
	s_waitcnt vmcnt(4)
	v_add_u32_e32 v18, v18, v11
	s_waitcnt vmcnt(3)
	v_add_u32_e32 v18, v18, v12
	s_waitcnt vmcnt(2)
	v_add_u32_e32 v18, v18, v13
	s_waitcnt vmcnt(1)
	v_add_u32_e32 v18, v18, v14
	s_waitcnt vmcnt(0)
	v_add_u32_e32 v18, v18, v15
	v_cmp_eq_u32_e32 vcc, s0, v18
	s_cbranch_vccnz .LBB0_45
	s_and_b32 s2, s1, 0xff
	s_cmp_eq_u32 s2, 0
	s_mov_b64 s[50:51], -1
	s_cbranch_scc1 .LBB0_50
	s_and_b64 vcc, exec, s[50:51]
	s_cbranch_vccz .LBB0_45

.LBB0_64:
	s_and_b32 s1, s0, 0xff
	s_mov_b64 s[22:23], -1
	s_cmp_lg_u32 s1, 0
	s_mov_b64 s[26:27], -1
	s_cbranch_scc0 .LBB0_67
	s_and_b64 vcc, exec, s[26:27]
	s_cbranch_vccz .LBB0_63

.LBB0_81:
	s_and_b32 s1, s0, 0xff
	s_cmp_lg_u32 s1, 0
	s_mov_b64 s[24:25], -1
	s_cbranch_scc0 .LBB0_84
	s_mov_b64 s[26:27], -1
	s_and_b64 vcc, exec, s[24:25]
	s_cbranch_vccz .LBB0_80

.LBB0_1079:
	s_or_b64 exec, exec, s[30:31]
	s_and_b32 s30, s3, 1
	s_cmp_lg_u32 s47, s30
	s_cbranch_scc1 .LBB0_1089
	v_mov_b32_e32 v130, 0x3fffff
	buffer_inv sc1
	s_branch .LBB0_1082
.LBB0_1081:
	s_cbranch_execz .LBB0_1084
.LBB0_1082:
	global_load_dword v131, v[132:133], off sc1
	v_subrev_co_u32_e32 v130, vcc, 1, v130
	s_waitcnt vmcnt(0)
	v_readfirstlane_b32 s30, v131
	s_cmp_gt_u32 s30, 31
	s_cselect_b64 s[30:31], -1, 0
	s_or_b64 s[30:31], s[30:31], vcc
	s_and_b64 vcc, exec, s[30:31]
	s_cbranch_vccz .LBB0_1081

.LBB0_1397:
	s_or_b64 exec, exec, s[40:41]
	s_and_b32 s37, s63, 1
	s_cmp_lg_u32 s35, s37
	s_cbranch_scc1 .LBB0_1407
	v_mov_b32_e32 v128, 0x3fffff
	buffer_inv sc1
	s_branch .LBB0_1400
.LBB0_1399:
	s_cbranch_execz .LBB0_1402
.LBB0_1400:
	global_load_dword v129, v[132:133], off sc1
	v_subrev_co_u32_e32 v128, vcc, 1, v128
	s_waitcnt vmcnt(0)
	v_readfirstlane_b32 s35, v129
	s_cmp_gt_u32 s35, 31
	s_cselect_b64 s[40:41], -1, 0
	s_or_b64 s[40:41], s[40:41], vcc
	s_and_b64 vcc, exec, s[40:41]
	s_cbranch_vccz .LBB0_1399
